# store-drain epilogue plus next-tile LDS-DMA with instruction offsets and m0 written ahead of the fragment reads (11 fewer scalar instrs per first-half P.V)
# baseline (speedup 1.0000x reference)
.Lv4_cont_h1:
	v_add_f32_e32 v224, v224, v188
	s_barrier
	s_setprio 0
	s_waitcnt lgkmcnt(2)
	v_mfma_f32_32x32x16_bf16 v[4:19], v[152:155], v[184:187], v[4:19]
	ds_read_b64_tr_b16 v[156:157], v3 offset:33792
	ds_read_b64_tr_b16 v[158:159], v3 offset:37888
	s_waitcnt lgkmcnt(2)
	v_mfma_f32_32x32x16_bf16 v[116:131], v[152:155], v[180:183], v[116:131]
	s_add_i32 m0, s80, 0x4000
	ds_read_b64_tr_b16 v[160:161], v3 offset:34304
	ds_read_b64_tr_b16 v[162:163], v3 offset:38400
	global_load_lds_dwordx4 v200, s[86:87]
	s_waitcnt lgkmcnt(2)
	v_mfma_f32_32x32x16_bf16 v[100:115], v[152:155], v[156:159], v[100:115]
	ds_read_b64_tr_b16 v[156:157], v3 offset:34816
	ds_read_b64_tr_b16 v[158:159], v3 offset:38912
	s_waitcnt lgkmcnt(2)
	v_mfma_f32_32x32x16_bf16 v[84:99], v[152:155], v[160:163], v[84:99]
	s_add_i32 m0, s81, 0x10000
	ds_read_b64_tr_b16 v[160:161], v3 offset:35328
	ds_read_b64_tr_b16 v[162:163], v3 offset:39424
	global_load_lds_dwordx4 v204, s[2:3]
	s_waitcnt lgkmcnt(2)
	v_mfma_f32_32x32x16_bf16 v[68:83], v[152:155], v[156:159], v[68:83]
	ds_read_b64_tr_b16 v[156:157], v3 offset:35840
	ds_read_b64_tr_b16 v[158:159], v3 offset:39936
	s_waitcnt lgkmcnt(2)
	v_mfma_f32_32x32x16_bf16 v[52:67], v[152:155], v[160:163], v[52:67]
	s_add_i32 m0, s81, 0x10380
	ds_read_b64_tr_b16 v[160:161], v3 offset:36352
	ds_read_b64_tr_b16 v[162:163], v3 offset:40448
	global_load_lds_dwordx4 v204, s[2:3] offset:128
	s_waitcnt lgkmcnt(2)
	v_mfma_f32_32x32x16_bf16 v[36:51], v[152:155], v[156:159], v[36:51]
	ds_read_b64_tr_b16 v[156:157], v3 offset:40960
	ds_read_b64_tr_b16 v[158:159], v3 offset:45056
	s_waitcnt lgkmcnt(2)
	v_mfma_f32_32x32x16_bf16 v[20:35], v[152:155], v[160:163], v[20:35]
	s_add_i32 m0, s81, 0x10700
	ds_read_b64_tr_b16 v[152:153], v3 offset:41472
	ds_read_b64_tr_b16 v[154:155], v3 offset:45568
	global_load_lds_dwordx4 v204, s[2:3] offset:256
	s_waitcnt lgkmcnt(2)
	v_mfma_f32_32x32x16_bf16 v[4:19], v[148:151], v[156:159], v[4:19]
	ds_read_b64_tr_b16 v[156:157], v3 offset:41984
	ds_read_b64_tr_b16 v[158:159], v3 offset:46080
	s_waitcnt lgkmcnt(2)
	v_mfma_f32_32x32x16_bf16 v[116:131], v[148:151], v[152:155], v[116:131]
	s_add_i32 m0, s81, 0x10a80
	ds_read_b64_tr_b16 v[152:153], v3 offset:42496
	ds_read_b64_tr_b16 v[154:155], v3 offset:46592
	global_load_lds_dwordx4 v204, s[2:3] offset:384
	s_waitcnt lgkmcnt(2)
	v_mfma_f32_32x32x16_bf16 v[100:115], v[148:151], v[156:159], v[100:115]
	ds_read_b64_tr_b16 v[156:157], v3 offset:43008
	ds_read_b64_tr_b16 v[158:159], v3 offset:47104
	s_waitcnt lgkmcnt(2)
	v_mfma_f32_32x32x16_bf16 v[84:99], v[148:151], v[152:155], v[84:99]
	ds_read_b64_tr_b16 v[152:153], v3 offset:43520
	ds_read_b64_tr_b16 v[154:155], v3 offset:47616
	s_waitcnt lgkmcnt(2)
	v_mfma_f32_32x32x16_bf16 v[68:83], v[148:151], v[156:159], v[68:83]
	ds_read_b64_tr_b16 v[156:157], v3 offset:44032
	ds_read_b64_tr_b16 v[158:159], v3 offset:48128
	s_waitcnt lgkmcnt(2)
	v_mfma_f32_32x32x16_bf16 v[52:67], v[148:151], v[152:155], v[52:67]
	ds_read_b64_tr_b16 v[152:153], v3 offset:44544
	ds_read_b64_tr_b16 v[154:155], v3 offset:48640
	s_waitcnt lgkmcnt(2)
	v_mfma_f32_32x32x16_bf16 v[36:51], v[148:151], v[156:159], v[36:51]
	s_waitcnt lgkmcnt(0)
	v_mfma_f32_32x32x16_bf16 v[20:35], v[148:151], v[152:155], v[20:35]
	s_barrier
	s_setprio 1
	ds_read_b128 v[180:183], v225 offset:4096
	ds_read_b128 v[184:187], v226 offset:4096
	s_waitcnt lgkmcnt(1)
	v_mfma_i32_32x32x32_i8 v[148:163], v[180:183], v[164:167], v[132:147]
	ds_read_b128 v[180:183], v227 offset:4096
	s_waitcnt lgkmcnt(1)
	v_mfma_i32_32x32x32_i8 v[148:163], v[184:187], v[168:171], v[148:163]
	ds_read_b128 v[188:191], v228 offset:4096
	s_waitcnt lgkmcnt(1)
	v_mfma_i32_32x32x32_i8 v[148:163], v[180:183], v[172:175], v[148:163]
	ds_read_b64_tr_b16 v[184:185], v3 offset:49152
	ds_read_b64_tr_b16 v[186:187], v3 offset:53248
	s_waitcnt lgkmcnt(2)
	v_mfma_i32_32x32x32_i8 v[148:163], v[188:191], v[176:179], v[148:163]
	ds_read_b64_tr_b16 v[180:181], v3 offset:49664
	ds_read_b64_tr_b16 v[182:183], v3 offset:53760
	s_nop 7
	v_mul_f32_e32 v189, v221, v207
	v_fma_f32 v190, s100, v189, v255
	v_fma_f32 v148, v148, v189, -v190
	v_fma_f32 v149, v149, v189, -v190
	v_exp_f32_e32 v148, v148
	v_fma_f32 v150, v150, v189, -v190
	v_exp_f32_e32 v149, v149
	v_fma_f32 v151, v151, v189, -v190
	v_exp_f32_e32 v150, v150
	v_fma_f32 v152, v152, v189, -v190
	v_exp_f32_e32 v151, v151
	v_fma_f32 v153, v153, v189, -v190
	v_exp_f32_e32 v152, v152
	v_fma_f32 v154, v154, v189, -v190
	v_exp_f32_e32 v153, v153
	v_fma_f32 v155, v155, v189, -v190
	v_exp_f32_e32 v154, v154
	v_fma_f32 v156, v156, v189, -v190
	v_exp_f32_e32 v155, v155
	v_fma_f32 v157, v157, v189, -v190
	v_exp_f32_e32 v156, v156
	v_fma_f32 v158, v158, v189, -v190
	v_exp_f32_e32 v157, v157
	v_fma_f32 v159, v159, v189, -v190
	v_exp_f32_e32 v158, v158
	v_fma_f32 v160, v160, v189, -v190
	v_exp_f32_e32 v159, v159
	v_fma_f32 v161, v161, v189, -v190
	v_exp_f32_e32 v160, v160
	v_fma_f32 v162, v162, v189, -v190
	v_exp_f32_e32 v161, v161
	v_fma_f32 v163, v163, v189, -v190
	v_exp_f32_e32 v162, v162
	v_exp_f32_e32 v163, v163
	v_add_f32_e32 v188, v148, v149
	v_add_f32_e32 v189, v150, v151
	v_add_f32_e32 v190, v152, v153
	v_add_f32_e32 v191, v154, v155
	v_add_f32_e32 v192, v156, v157
	v_add_f32_e32 v193, v158, v159
	v_add_f32_e32 v194, v160, v161
	v_add_f32_e32 v195, v162, v163
	v_add_f32_e32 v188, v188, v189
	v_add_f32_e32 v190, v190, v191
	v_add_f32_e32 v192, v192, v193
	v_add_f32_e32 v194, v194, v195
	v_add_f32_e32 v188, v188, v190
	v_add_f32_e32 v192, v192, v194
	v_add_f32_e32 v188, v188, v192
	v_cmp_lt_f32_e32 vcc, s101, v188
	v_cvt_pk_bf16_f32 v155, v154, v155
	v_cvt_pk_bf16_f32 v154, v152, v153
	v_cvt_pk_bf16_f32 v152, v148, v149
	v_cvt_pk_bf16_f32 v153, v150, v151
	v_cvt_pk_bf16_f32 v148, v156, v157
	v_cvt_pk_bf16_f32 v149, v158, v159
	v_cvt_pk_bf16_f32 v150, v160, v161
	v_cvt_pk_bf16_f32 v151, v162, v163
	s_cbranch_vccnz .Lv4_rare_h2

.Lv4_cont_h3:
	v_add_f32_e32 v224, v224, v188
	s_barrier
	s_setprio 0
	s_waitcnt lgkmcnt(2)
	v_mfma_f32_32x32x16_bf16 v[4:19], v[152:155], v[184:187], v[4:19]
	ds_read_b64_tr_b16 v[156:157], v222 offset:33792
	ds_read_b64_tr_b16 v[158:159], v222 offset:37888
	s_waitcnt lgkmcnt(2)
	v_mfma_f32_32x32x16_bf16 v[116:131], v[152:155], v[180:183], v[116:131]
	s_add_i32 m0, s83, 0
	ds_read_b64_tr_b16 v[160:161], v222 offset:34304
	ds_read_b64_tr_b16 v[162:163], v222 offset:38400
	global_load_lds_dwordx4 v200, s[86:87]
	s_waitcnt lgkmcnt(2)
	v_mfma_f32_32x32x16_bf16 v[100:115], v[152:155], v[156:159], v[100:115]
	ds_read_b64_tr_b16 v[156:157], v222 offset:34816
	ds_read_b64_tr_b16 v[158:159], v222 offset:38912
	s_waitcnt lgkmcnt(2)
	v_mfma_f32_32x32x16_bf16 v[84:99], v[152:155], v[160:163], v[84:99]
	s_add_i32 m0, s82, 0
	ds_read_b64_tr_b16 v[160:161], v222 offset:35328
	ds_read_b64_tr_b16 v[162:163], v222 offset:39424
	global_load_lds_dwordx4 v204, s[2:3]
	s_waitcnt lgkmcnt(2)
	v_mfma_f32_32x32x16_bf16 v[68:83], v[152:155], v[156:159], v[68:83]
	ds_read_b64_tr_b16 v[156:157], v222 offset:35840
	ds_read_b64_tr_b16 v[158:159], v222 offset:39936
	s_waitcnt lgkmcnt(2)
	v_mfma_f32_32x32x16_bf16 v[52:67], v[152:155], v[160:163], v[52:67]
	s_add_i32 m0, s82, 0x380
	ds_read_b64_tr_b16 v[160:161], v222 offset:36352
	ds_read_b64_tr_b16 v[162:163], v222 offset:40448
	global_load_lds_dwordx4 v204, s[2:3] offset:128
	s_waitcnt lgkmcnt(2)
	v_mfma_f32_32x32x16_bf16 v[36:51], v[152:155], v[156:159], v[36:51]
	ds_read_b64_tr_b16 v[156:157], v222 offset:40960
	ds_read_b64_tr_b16 v[158:159], v222 offset:45056
	s_waitcnt lgkmcnt(2)
	v_mfma_f32_32x32x16_bf16 v[20:35], v[152:155], v[160:163], v[20:35]
	s_add_i32 m0, s82, 0x700
	ds_read_b64_tr_b16 v[152:153], v222 offset:41472
	ds_read_b64_tr_b16 v[154:155], v222 offset:45568
	global_load_lds_dwordx4 v204, s[2:3] offset:256
	s_waitcnt lgkmcnt(2)
	v_mfma_f32_32x32x16_bf16 v[4:19], v[148:151], v[156:159], v[4:19]
	ds_read_b64_tr_b16 v[156:157], v222 offset:41984
	ds_read_b64_tr_b16 v[158:159], v222 offset:46080
	s_waitcnt lgkmcnt(2)
	v_mfma_f32_32x32x16_bf16 v[116:131], v[148:151], v[152:155], v[116:131]
	s_add_i32 m0, s82, 0xa80
	ds_read_b64_tr_b16 v[152:153], v222 offset:42496
	ds_read_b64_tr_b16 v[154:155], v222 offset:46592
	global_load_lds_dwordx4 v204, s[2:3] offset:384
	s_waitcnt lgkmcnt(2)
	v_mfma_f32_32x32x16_bf16 v[100:115], v[148:151], v[156:159], v[100:115]
	ds_read_b64_tr_b16 v[156:157], v222 offset:43008
	ds_read_b64_tr_b16 v[158:159], v222 offset:47104
	s_waitcnt lgkmcnt(2)
	v_mfma_f32_32x32x16_bf16 v[84:99], v[148:151], v[152:155], v[84:99]
	ds_read_b64_tr_b16 v[152:153], v222 offset:43520
	ds_read_b64_tr_b16 v[154:155], v222 offset:47616
	s_waitcnt lgkmcnt(2)
	v_mfma_f32_32x32x16_bf16 v[68:83], v[148:151], v[156:159], v[68:83]
	ds_read_b64_tr_b16 v[156:157], v222 offset:44032
	ds_read_b64_tr_b16 v[158:159], v222 offset:48128
	s_waitcnt lgkmcnt(2)
	v_mfma_f32_32x32x16_bf16 v[52:67], v[148:151], v[152:155], v[52:67]
	ds_read_b64_tr_b16 v[152:153], v222 offset:44544
	ds_read_b64_tr_b16 v[154:155], v222 offset:48640
	s_waitcnt lgkmcnt(2)
	v_mfma_f32_32x32x16_bf16 v[36:51], v[148:151], v[156:159], v[36:51]
	s_waitcnt lgkmcnt(0)
	v_mfma_f32_32x32x16_bf16 v[20:35], v[148:151], v[152:155], v[20:35]
	s_barrier
	s_setprio 1
	ds_read_b128 v[180:183], v225 offset:20480
	ds_read_b128 v[184:187], v226 offset:20480
	s_waitcnt lgkmcnt(1)
	v_mfma_i32_32x32x32_i8 v[148:163], v[180:183], v[164:167], v[132:147]
	ds_read_b128 v[180:183], v227 offset:20480
	s_waitcnt lgkmcnt(1)
	v_mfma_i32_32x32x32_i8 v[148:163], v[184:187], v[168:171], v[148:163]
	ds_read_b128 v[188:191], v228 offset:20480
	s_waitcnt lgkmcnt(1)
	v_mfma_i32_32x32x32_i8 v[148:163], v[180:183], v[172:175], v[148:163]
	ds_read_b64_tr_b16 v[184:185], v222 offset:49152
	ds_read_b64_tr_b16 v[186:187], v222 offset:53248
	s_waitcnt lgkmcnt(2)
	v_mfma_i32_32x32x32_i8 v[148:163], v[188:191], v[176:179], v[148:163]
	ds_read_b64_tr_b16 v[180:181], v222 offset:49664
	ds_read_b64_tr_b16 v[182:183], v222 offset:53760
	s_nop 7
	v_mul_f32_e32 v189, v221, v236
	v_fma_f32 v190, s100, v189, v255
	v_fma_f32 v148, v148, v189, -v190
	v_fma_f32 v149, v149, v189, -v190
	v_exp_f32_e32 v148, v148
	v_fma_f32 v150, v150, v189, -v190
	v_exp_f32_e32 v149, v149
	v_fma_f32 v151, v151, v189, -v190
	v_exp_f32_e32 v150, v150
	v_fma_f32 v152, v152, v189, -v190
	v_exp_f32_e32 v151, v151
	v_fma_f32 v153, v153, v189, -v190
	v_exp_f32_e32 v152, v152
	v_fma_f32 v154, v154, v189, -v190
	v_exp_f32_e32 v153, v153
	v_fma_f32 v155, v155, v189, -v190
	v_exp_f32_e32 v154, v154
	v_fma_f32 v156, v156, v189, -v190
	v_exp_f32_e32 v155, v155
	v_fma_f32 v157, v157, v189, -v190
	v_exp_f32_e32 v156, v156
	v_fma_f32 v158, v158, v189, -v190
	v_exp_f32_e32 v157, v157
	v_fma_f32 v159, v159, v189, -v190
	v_exp_f32_e32 v158, v158
	v_fma_f32 v160, v160, v189, -v190
	v_exp_f32_e32 v159, v159
	v_fma_f32 v161, v161, v189, -v190
	v_exp_f32_e32 v160, v160
	v_fma_f32 v162, v162, v189, -v190
	v_exp_f32_e32 v161, v161
	v_fma_f32 v163, v163, v189, -v190
	v_exp_f32_e32 v162, v162
	v_exp_f32_e32 v163, v163
	v_add_f32_e32 v188, v148, v149
	v_add_f32_e32 v189, v150, v151
	v_add_f32_e32 v190, v152, v153
	v_add_f32_e32 v191, v154, v155
	v_add_f32_e32 v192, v156, v157
	v_add_f32_e32 v193, v158, v159
	v_add_f32_e32 v194, v160, v161
	v_add_f32_e32 v195, v162, v163
	v_add_f32_e32 v188, v188, v189
	v_add_f32_e32 v190, v190, v191
	v_add_f32_e32 v192, v192, v193
	v_add_f32_e32 v194, v194, v195
	v_add_f32_e32 v188, v188, v190
	v_add_f32_e32 v192, v192, v194
	v_add_f32_e32 v188, v188, v192
	v_cmp_lt_f32_e32 vcc, s101, v188
	v_cvt_pk_bf16_f32 v155, v154, v155
	v_cvt_pk_bf16_f32 v154, v152, v153
	v_cvt_pk_bf16_f32 v152, v148, v149
	v_cvt_pk_bf16_f32 v153, v150, v151
	v_cvt_pk_bf16_f32 v148, v156, v157
	v_cvt_pk_bf16_f32 v149, v158, v159
	v_cvt_pk_bf16_f32 v150, v160, v161
	v_cvt_pk_bf16_f32 v151, v162, v163
	s_cbranch_vccnz .Lv4_rare_h4
